# compressed-branch pass 2: the per-row max subtraction is folded into the QK MFMA accumulator init (16 fewer VALU per key tile)
# baseline (speedup 1.0000x reference)
; #define LDS_WAIT() asm volatile("s_waitcnt lgkmcnt(0)" ::: "memory")
; __device__ __forceinline__ float xhalf_sum(float v) { const auto r = __builtin_amdgcn_permlane32_swap(__float_as_uint(v), __float_as_uint(v), false, false); return __uint_as_float(r[0]) + __uint_as_float(r[1]); }
; #define CMP_LDK(KF, KT) do { const int kn_ = ((KT) < ntile) ? (KT) : ntile - 1; _Pragma("unroll") for (int s = 0; s < 4; ++s) KF[s] = kb[kn_ * 256 + s * 64]; } while (0)
; __device__ __forceinline__ void nsa_tile(const Ctx& C, int b, int g, int t0) {
;     ...
;         l1 = xhalf_sum(l1);
;         const float inv = 1.f / fmaxf(l1, 1e-30f), m1sub = (m1 < -1e29f) ? 0.f : m1;
;         for (int e = lane; e < 8 * 264; e += 64) imp[e] = 0.f;
;         LDS_WAIT();
;         f32x16 O[2];
; #pragma unroll
;         for (int i = 0; i < 16; ++i) { O[0][i] = 0.f; O[1][i] = 0.f; }
;     ...
;         if (ntile > 0) {
;             bf16x8 kA[4], kB[4], kC[4], vA[4];
;     ...
;             CMP_LDK(kA, 0); CMP_LDK(kB, 1);
.LBB0_688:
	s_or_b64 exec, exec, s[2:3]
	s_waitcnt lgkmcnt(0)
	s_and_b64 vcc, exec, s[0:1]
	s_cbranch_vccz .LBB0_729
	s_add_u32 s0, s28, s22
	s_addc_u32 s1, s77, s23
	s_cmp_eq_u32 s16, 1
	s_mov_b32 s13, 0
	s_cselect_b32 s12, 0, 0x1000
	v_lshl_add_u64 v[4:5], v[180:181], 0, s[12:13]
	global_load_dwordx4 v[126:129], v[180:181], off
	global_load_dwordx4 v[122:125], v[180:181], off offset:1024
	global_load_dwordx4 v[118:121], v[180:181], off offset:2048
	global_load_dwordx4 v[114:117], v[180:181], off offset:3072
	global_load_dwordx4 v[142:145], v[4:5], off
	global_load_dwordx4 v[138:141], v[4:5], off offset:1024
	global_load_dwordx4 v[134:137], v[4:5], off offset:2048
	global_load_dwordx4 v[130:133], v[4:5], off offset:3072
	v_add_f32_e32 v2, v90, v2
	v_max_f32_e32 v2, 0xda24260, v2
	v_div_scale_f32 v3, s[2:3], v2, v2, 1.0
	v_rcp_f32_e32 v4, v3
	v_cmp_eq_u32_e64 s[4:5], 1, v244
	s_mov_b32 s58, 4
	v_lshl_add_u64 v[184:185], v[224:225], 4, s[0:1]
	v_fma_f32 v5, -v3, v4, 1.0
	v_fmac_f32_e32 v4, v5, v4
	v_div_scale_f32 v5, vcc, 1.0, v2, 1.0
	v_mul_f32_e32 v6, v5, v4
	v_fma_f32 v7, -v3, v6, v5
	v_fmac_f32_e32 v6, v7, v4
	v_fma_f32 v3, -v3, v6, v5
	v_div_fmas_f32 v3, v3, v4, v6
	v_div_fixup_f32 v182, v3, v2, 1.0
	v_cmp_ngt_f32_e32 vcc, s66, v88
	v_mul_u32_u24_e32 v3, 0x420, v82
	v_mov_b32_e32 v2, 0
	v_cndmask_b32_e32 v187, 0, v88, vcc
	v_sub_f32_e32 v226, 0, v187
	v_mov_b32_e32 v227, v226
	v_mov_b32_e32 v228, v226
	v_mov_b32_e32 v229, v226
	v_mov_b32_e32 v230, v226
	v_mov_b32_e32 v231, v226
	v_mov_b32_e32 v232, v226
	v_mov_b32_e32 v233, v226
	v_mov_b32_e32 v234, v226
	v_mov_b32_e32 v235, v226
	v_mov_b32_e32 v236, v226
	v_mov_b32_e32 v237, v226
	v_mov_b32_e32 v238, v226
	v_mov_b32_e32 v239, v226
	v_mov_b32_e32 v240, v226
	v_mov_b32_e32 v241, v226
	v_cmp_eq_u32_e32 vcc, 0, v83
	v_add3_u32 v188, s73, v3, v218
	v_and_b32_e32 v3, 0xffffffe3, v224
	s_add_i32 s12, s16, -1
	s_sub_i32 s17, s17, 32
	v_cmp_eq_u32_e64 s[0:1], 0, v3
	s_and_b64 s[4:5], vcc, s[4:5]
	v_mov_b32_e32 v183, v182
	v_add_u32_e32 v189, -1, v85
	s_movk_i32 s18, 0x100
	v_mov_b32_e32 v3, v2
	v_mov_b32_e32 v4, v2
	v_mov_b32_e32 v5, v2
	v_mov_b32_e32 v6, v2
	v_mov_b32_e32 v7, v2
	v_mov_b32_e32 v8, v2
	v_mov_b32_e32 v9, v2
	v_mov_b32_e32 v10, v2
	v_mov_b32_e32 v11, v2
	v_mov_b32_e32 v12, v2
	v_mov_b32_e32 v13, v2
	v_mov_b32_e32 v14, v2
	v_mov_b32_e32 v15, v2
	v_mov_b32_e32 v16, v2
	v_mov_b32_e32 v17, v2
	s_waitcnt vmcnt(8)
	v_mov_b32_e32 v18, v2
	v_mov_b32_e32 v19, v2
	v_mov_b32_e32 v20, v2
	v_mov_b32_e32 v21, v2
	v_mov_b32_e32 v22, v2
	v_mov_b32_e32 v23, v2
	v_mov_b32_e32 v24, v2
	v_mov_b32_e32 v25, v2
	v_mov_b32_e32 v26, v2
	v_mov_b32_e32 v27, v2
	v_mov_b32_e32 v28, v2
	v_mov_b32_e32 v29, v2
	v_mov_b32_e32 v30, v2
	v_mov_b32_e32 v31, v2
	v_mov_b32_e32 v32, v2
	v_mov_b32_e32 v33, v2
	s_branch .LBB0_692

.LBB0_692:
	s_add_i32 s6, s58, -2
	s_cmp_lt_u32 s6, s16
	s_cselect_b64 s[24:25], -1, 0
	s_and_b64 s[2:3], s[24:25], exec
	s_cselect_b32 s2, s6, s12
	s_lshl_b32 s2, s2, 8
	s_ashr_i32 s3, s2, 31
	v_lshl_add_u64 v[34:35], s[2:3], 4, v[180:181]
	s_add_i32 s6, s18, 0xffffff00
	global_load_dwordx4 v[158:161], v[34:35], off
	global_load_dwordx4 v[154:157], v[34:35], off offset:1024
	global_load_dwordx4 v[150:153], v[34:35], off offset:2048
	global_load_dwordx4 v[146:149], v[34:35], off offset:3072
	v_lshl_add_u64 v[34:35], s[6:7], 4, v[184:185]
	global_load_dwordx4 v[58:61], v[34:35], off
	global_load_dwordx4 v[54:57], v[34:35], off offset:1024
	global_load_dwordx4 v[50:53], v[34:35], off offset:2048
	global_load_dwordx4 v[66:69], v[34:35], off offset:3072
	s_waitcnt vmcnt(15)
	v_mfma_f32_32x32x16_bf16 v[34:49], v[126:129], v[98:101], v[226:241]
	s_cmp_le_i32 s13, s17
	s_waitcnt vmcnt(14)
	v_mfma_f32_32x32x16_bf16 v[34:49], v[122:125], v[102:105], v[34:49]
	s_waitcnt vmcnt(13)
	v_mfma_f32_32x32x16_bf16 v[34:49], v[118:121], v[106:109], v[34:49]
	s_waitcnt vmcnt(12)
	v_mfma_f32_32x32x16_bf16 v[34:49], v[114:117], v[110:113], v[34:49]
	s_cbranch_scc1 .LBB0_694
	v_cmp_lt_i32_e32 vcc, -1, v189
	v_max_i32_e32 v63, 0, v189
	s_nop 0
	v_cndmask_b32_e32 v62, 64, v218, vcc
	v_cmp_le_u32_e32 vcc, v62, v63
	v_or_b32_e32 v64, 2, v62
	s_nop 4
	v_cndmask_b32_e32 v34, v249, v34, vcc
	v_cmp_lt_u32_e32 vcc, v62, v63
	s_nop 1
	v_cndmask_b32_e32 v35, v249, v35, vcc
	v_cmp_le_u32_e32 vcc, v64, v63
	v_or_b32_e32 v64, 3, v62
	s_nop 0
	v_cndmask_b32_e32 v36, v249, v36, vcc
	v_cmp_le_u32_e32 vcc, v64, v63
	v_or_b32_e32 v64, 4, v62
	s_nop 0
	v_cndmask_b32_e32 v37, v249, v37, vcc
	v_cmp_le_u32_e32 vcc, v64, v63
	v_or_b32_e32 v64, 5, v62
	s_nop 0
	v_cndmask_b32_e32 v38, v249, v38, vcc
	v_cmp_le_u32_e32 vcc, v64, v63
	v_or_b32_e32 v64, 6, v62
	s_nop 0
	v_cndmask_b32_e32 v39, v249, v39, vcc
	v_cmp_le_u32_e32 vcc, v64, v63
	v_or_b32_e32 v64, 7, v62
	s_nop 0
	v_cndmask_b32_e32 v40, v249, v40, vcc
	v_cmp_le_u32_e32 vcc, v64, v63
	v_add_u32_e32 v64, 16, v62
	s_nop 0
	v_cndmask_b32_e32 v41, v249, v41, vcc
	v_cmp_le_u32_e32 vcc, v64, v63
	v_add_u32_e32 v64, 17, v62
	s_nop 0
	v_cndmask_b32_e32 v42, v249, v42, vcc
	v_cmp_le_u32_e32 vcc, v64, v63
	v_add_u32_e32 v64, 18, v62
	s_nop 0
	v_cndmask_b32_e32 v43, v249, v43, vcc
	v_cmp_le_u32_e32 vcc, v64, v63
	v_add_u32_e32 v64, 19, v62
	s_nop 0
	v_cndmask_b32_e32 v44, v249, v44, vcc
	v_cmp_le_u32_e32 vcc, v64, v63
	v_add_u32_e32 v64, 20, v62
	s_nop 0
	v_cndmask_b32_e32 v45, v249, v45, vcc
	v_cmp_le_u32_e32 vcc, v64, v63
	v_add_u32_e32 v64, 21, v62
	s_nop 0
	v_cndmask_b32_e32 v46, v249, v46, vcc
	v_cmp_le_u32_e32 vcc, v64, v63
	v_add_u32_e32 v64, 22, v62
	v_add_u32_e32 v62, 23, v62
	v_cndmask_b32_e32 v47, v249, v47, vcc
	v_cmp_le_u32_e32 vcc, v64, v63
	s_nop 1
	v_cndmask_b32_e32 v48, v249, v48, vcc
	v_cmp_le_u32_e32 vcc, v62, v63
	s_nop 1
	v_cndmask_b32_e32 v49, v249, v49, vcc
.LBB0_694:
	s_nop 10
	v_exp_f32_e32 v36, v36
	v_exp_f32_e32 v37, v37
	v_exp_f32_e32 v38, v38
	v_exp_f32_e32 v39, v39
	v_exp_f32_e32 v34, v34
	v_exp_f32_e32 v35, v35
	v_exp_f32_e32 v40, v40
	v_exp_f32_e32 v41, v41
	v_pk_mul_f32 v[36:37], v[182:183], v[36:37]
	v_pk_mul_f32 v[38:39], v[182:183], v[38:39]
	v_pk_mul_f32 v[34:35], v[182:183], v[34:35]
	v_fma_f32 v63, 0.5, v37, v38
	v_pk_mul_f32 v[40:41], v[182:183], v[40:41]
	v_add_f32_e32 v62, v34, v35
	v_add_f32_e32 v63, v39, v63
	v_add_f32_e32 v62, v36, v62
	v_add_f32_e32 v63, v40, v63
	v_mul_f32_e32 v64, 0.5, v41
	v_fmac_f32_e32 v62, 0.5, v37
	v_fmac_f32_e32 v63, 0.5, v41
	v_mov_b32_dpp v64, v64 quad_perm:[1,0,3,2] row_mask:0xf bank_mask:0xf bound_ctrl:1
	v_add_f32_dpp v62, v62, v62 quad_perm:[1,0,3,2] row_mask:0xf bank_mask:0xf bound_ctrl:1
	v_add_f32_dpp v63, v63, v63 quad_perm:[1,0,3,2] row_mask:0xf bank_mask:0xf bound_ctrl:1
	v_fmac_f32_e32 v64, 0.5, v41
	v_add_f32_dpp v62, v62, v62 quad_perm:[2,3,0,1] row_mask:0xf bank_mask:0xf bound_ctrl:1
	v_add_f32_dpp v63, v63, v63 quad_perm:[2,3,0,1] row_mask:0xf bank_mask:0xf bound_ctrl:1
	v_add_f32_dpp v64, v64, v64 quad_perm:[2,3,0,1] row_mask:0xf bank_mask:0xf bound_ctrl:1
	v_add_u32_e32 v190, s13, v188
	s_and_saveexec_b64 s[2:3], s[0:1]
	s_cbranch_execz .LBB0_696
	ds_add_f32 v190, v62
	ds_add_f32 v190, v63 offset:4
	ds_add_f32 v190, v64 offset:8

.LBB0_698:
	s_or_b64 exec, exec, s[2:3]
	v_exp_f32_e32 v44, v44
	v_exp_f32_e32 v45, v45
	v_exp_f32_e32 v46, v46
	v_exp_f32_e32 v47, v47
	v_exp_f32_e32 v42, v42
	v_exp_f32_e32 v43, v43
	v_exp_f32_e32 v48, v48
	v_exp_f32_e32 v49, v49
	v_pk_mul_f32 v[44:45], v[182:183], v[44:45]
	v_pk_mul_f32 v[46:47], v[182:183], v[46:47]
	v_pk_mul_f32 v[42:43], v[182:183], v[42:43]
	v_fma_f32 v63, 0.5, v45, v46
	v_pk_mul_f32 v[48:49], v[182:183], v[48:49]
	v_add_f32_e32 v62, v42, v43
	v_add_f32_e32 v63, v47, v63
	v_add_f32_e32 v62, v44, v62
	v_add_f32_e32 v63, v48, v63
	v_mul_f32_e32 v64, 0.5, v49
	v_fmac_f32_e32 v62, 0.5, v45
	v_fmac_f32_e32 v63, 0.5, v49
	v_mov_b32_dpp v64, v64 quad_perm:[1,0,3,2] row_mask:0xf bank_mask:0xf bound_ctrl:1
	v_add_f32_dpp v62, v62, v62 quad_perm:[1,0,3,2] row_mask:0xf bank_mask:0xf bound_ctrl:1
	v_add_f32_dpp v63, v63, v63 quad_perm:[1,0,3,2] row_mask:0xf bank_mask:0xf bound_ctrl:1
	v_fmac_f32_e32 v64, 0.5, v49
	v_add_f32_dpp v62, v62, v62 quad_perm:[2,3,0,1] row_mask:0xf bank_mask:0xf bound_ctrl:1
	v_add_f32_dpp v63, v63, v63 quad_perm:[2,3,0,1] row_mask:0xf bank_mask:0xf bound_ctrl:1
	v_add_f32_dpp v64, v64, v64 quad_perm:[2,3,0,1] row_mask:0xf bank_mask:0xf bound_ctrl:1
	s_and_saveexec_b64 s[2:3], s[0:1]
	s_cbranch_execz .LBB0_700
	ds_add_f32 v190, v62 offset:16
	ds_add_f32 v190, v63 offset:20
	ds_add_f32 v190, v64 offset:24

; #define CMP_LDK(KF, KT) do { const int kn_ = ((KT) < ntile) ? (KT) : ntile - 1; _Pragma("unroll") for (int s = 0; s < 4; ++s) KF[s] = kb[kn_ * 256 + s * 64]; } while (0)
; #define CMP_LDV(KT) do { _Pragma("unroll") for (int s = 0; s < 4; ++s) vA[s] = vb[(KT) * 256 + s * 64]; } while (0)
; __device__ __forceinline__ void nsa_tile(const Ctx& C, int b, int g, int t0) {
;     ...
;         if (ntile > 0) {
;             bf16x8 kA[4], kB[4], kC[4], vA[4];
;     ...
;             CMP_LDK(kA, 0); CMP_LDK(kB, 1);
; #pragma unroll 1
;             for (int kt = 0; kt < ntile; kt += 3) {
;                 CMP_LDK(kC, kt + 2); CMP_LDV(kt);     __builtin_amdgcn_sched_barrier(0); CMP_P2(kA, vA, kt);     if (kt + 1 >= ntile) break;
;                 CMP_LDK(kA, kt + 3); CMP_LDV(kt + 1); __builtin_amdgcn_sched_barrier(0); CMP_P2(kB, vA, kt + 1); if (kt + 2 >= ntile) break;
;                 CMP_LDK(kB, kt + 4); CMP_LDV(kt + 2); __builtin_amdgcn_sched_barrier(0); CMP_P2(kC, vA, kt + 2);
.LBB0_702:
	s_or_b64 exec, exec, s[2:3]
	v_cvt_pk_bf16_f32 v34, v34, v35
	v_cvt_pk_bf16_f32 v35, v36, v37
	v_cvt_pk_bf16_f32 v36, v38, v39
	v_cvt_pk_bf16_f32 v37, v40, v41
	v_cvt_pk_bf16_f32 v70, v42, v43
	v_cvt_pk_bf16_f32 v71, v44, v45
	s_waitcnt vmcnt(3)
	v_mfma_f32_32x32x16_bf16 v[18:33], v[58:61], v[34:37], v[18:33]
	v_cvt_pk_bf16_f32 v72, v46, v47
	v_cvt_pk_bf16_f32 v73, v48, v49
	s_add_i32 s2, s58, -3
	s_cmp_ge_u32 s2, s16
	s_waitcnt vmcnt(2)
	v_mfma_f32_32x32x16_bf16 v[2:17], v[54:57], v[34:37], v[2:17]
	s_nop 5
	v_mov_b64_e32 v[48:49], v[32:33]
	v_mov_b64_e32 v[46:47], v[30:31]
	v_mov_b64_e32 v[44:45], v[28:29]
	v_mov_b64_e32 v[42:43], v[26:27]
	v_mov_b64_e32 v[40:41], v[24:25]
	v_mov_b64_e32 v[38:39], v[22:23]
	v_mov_b64_e32 v[36:37], v[20:21]
	v_mov_b64_e32 v[34:35], v[18:19]
	s_waitcnt vmcnt(1)
	s_nop 0
	v_mfma_f32_32x32x16_bf16 v[34:49], v[50:53], v[70:73], v[34:49]
	v_mov_b64_e32 v[64:65], v[16:17]
	v_mov_b64_e32 v[62:63], v[14:15]
	v_mov_b64_e32 v[60:61], v[12:13]
	v_mov_b64_e32 v[58:59], v[10:11]
	v_mov_b64_e32 v[56:57], v[8:9]
	v_mov_b64_e32 v[54:55], v[6:7]
	v_mov_b64_e32 v[52:53], v[4:5]
	v_mov_b64_e32 v[50:51], v[2:3]
	s_waitcnt vmcnt(0)
	s_nop 0
	v_mfma_f32_32x32x16_bf16 v[50:65], v[66:69], v[70:73], v[50:65]
	s_cbranch_scc1 .LBB0_690
	s_add_i32 s10, s58, -1
	s_cmp_lt_u32 s10, s16
	s_cselect_b32 s2, s10, s12
	s_lshl_b32 s2, s2, 8
	s_ashr_i32 s3, s2, 31
	v_lshl_add_u64 v[2:3], s[2:3], 4, v[180:181]
	s_mov_b32 s19, s7
	global_load_dwordx4 v[126:129], v[2:3], off
	global_load_dwordx4 v[122:125], v[2:3], off offset:1024
	global_load_dwordx4 v[118:121], v[2:3], off offset:2048
	global_load_dwordx4 v[114:117], v[2:3], off offset:3072
	v_lshl_add_u64 v[2:3], s[18:19], 4, v[184:185]
	global_load_dwordx4 v[26:29], v[2:3], off
	global_load_dwordx4 v[30:33], v[2:3], off offset:1024
	global_load_dwordx4 v[18:21], v[2:3], off offset:2048
	global_load_dwordx4 v[22:25], v[2:3], off offset:3072
	v_mfma_f32_32x32x16_bf16 v[2:17], v[142:145], v[98:101], v[226:241]
	s_add_i32 s2, s13, 32
	s_cmp_le_i32 s2, s17
	v_mfma_f32_32x32x16_bf16 v[2:17], v[138:141], v[102:105], v[2:17]
	v_mfma_f32_32x32x16_bf16 v[2:17], v[134:137], v[106:109], v[2:17]
	v_mfma_f32_32x32x16_bf16 v[2:17], v[130:133], v[110:113], v[2:17]
	s_cbranch_scc1 .LBB0_705
	v_subrev_u32_e32 v66, 32, v189
	v_cmp_lt_i32_e32 vcc, -1, v66
	v_max_i32_e32 v66, 0, v66
	s_nop 0
	v_cndmask_b32_e32 v67, 64, v218, vcc
	v_cmp_le_u32_e32 vcc, v67, v66
	v_or_b32_e32 v68, 2, v67
	s_nop 3
	v_cndmask_b32_e32 v2, v249, v2, vcc
	v_cmp_lt_u32_e32 vcc, v67, v66
	s_nop 1
	v_cndmask_b32_e32 v3, v249, v3, vcc
	v_cmp_le_u32_e32 vcc, v68, v66
	v_or_b32_e32 v68, 3, v67
	s_nop 0
	v_cndmask_b32_e32 v4, v249, v4, vcc
	v_cmp_le_u32_e32 vcc, v68, v66
	v_or_b32_e32 v68, 4, v67
	s_nop 0
	v_cndmask_b32_e32 v5, v249, v5, vcc
	v_cmp_le_u32_e32 vcc, v68, v66
	v_or_b32_e32 v68, 5, v67
	s_nop 0
	v_cndmask_b32_e32 v6, v249, v6, vcc
	v_cmp_le_u32_e32 vcc, v68, v66
	v_or_b32_e32 v68, 6, v67
	s_nop 0
	v_cndmask_b32_e32 v7, v249, v7, vcc
	v_cmp_le_u32_e32 vcc, v68, v66
	v_or_b32_e32 v68, 7, v67
	s_nop 0
	v_cndmask_b32_e32 v8, v249, v8, vcc
	v_cmp_le_u32_e32 vcc, v68, v66
	v_add_u32_e32 v68, 16, v67
	s_nop 0
	v_cndmask_b32_e32 v9, v249, v9, vcc
	v_cmp_le_u32_e32 vcc, v68, v66
	v_add_u32_e32 v68, 17, v67
	s_nop 0
	v_cndmask_b32_e32 v10, v249, v10, vcc
	v_cmp_le_u32_e32 vcc, v68, v66
	v_add_u32_e32 v68, 18, v67
	s_nop 0
	v_cndmask_b32_e32 v11, v249, v11, vcc
	v_cmp_le_u32_e32 vcc, v68, v66
	v_add_u32_e32 v68, 19, v67
	s_nop 0
	v_cndmask_b32_e32 v12, v249, v12, vcc
	v_cmp_le_u32_e32 vcc, v68, v66
	v_add_u32_e32 v68, 20, v67
	s_nop 0
	v_cndmask_b32_e32 v13, v249, v13, vcc
	v_cmp_le_u32_e32 vcc, v68, v66
	v_add_u32_e32 v68, 21, v67
	s_nop 0
	v_cndmask_b32_e32 v14, v249, v14, vcc
	v_cmp_le_u32_e32 vcc, v68, v66
	v_add_u32_e32 v68, 22, v67
	v_add_u32_e32 v67, 23, v67
	v_cndmask_b32_e32 v15, v249, v15, vcc
	v_cmp_le_u32_e32 vcc, v68, v66
	s_nop 1
	v_cndmask_b32_e32 v16, v249, v16, vcc
	v_cmp_le_u32_e32 vcc, v67, v66
	s_nop 1
	v_cndmask_b32_e32 v17, v249, v17, vcc
.LBB0_705:
	s_nop 10
	v_exp_f32_e32 v4, v4
	v_exp_f32_e32 v5, v5
	v_exp_f32_e32 v6, v6
	v_exp_f32_e32 v7, v7
	v_exp_f32_e32 v2, v2
	v_exp_f32_e32 v3, v3
	v_exp_f32_e32 v8, v8
	v_exp_f32_e32 v9, v9
	v_pk_mul_f32 v[4:5], v[182:183], v[4:5]
	v_pk_mul_f32 v[6:7], v[182:183], v[6:7]
	v_pk_mul_f32 v[2:3], v[182:183], v[2:3]
	v_fma_f32 v67, 0.5, v5, v6
	v_pk_mul_f32 v[8:9], v[182:183], v[8:9]
	v_add_f32_e32 v66, v2, v3
	v_add_f32_e32 v67, v7, v67
	v_add_f32_e32 v66, v4, v66
	v_add_f32_e32 v67, v8, v67
	v_mul_f32_e32 v68, 0.5, v9
	v_fmac_f32_e32 v66, 0.5, v5
	v_fmac_f32_e32 v67, 0.5, v9
	v_mov_b32_dpp v68, v68 quad_perm:[1,0,3,2] row_mask:0xf bank_mask:0xf bound_ctrl:1
	v_add_f32_dpp v66, v66, v66 quad_perm:[1,0,3,2] row_mask:0xf bank_mask:0xf bound_ctrl:1
	v_add_f32_dpp v67, v67, v67 quad_perm:[1,0,3,2] row_mask:0xf bank_mask:0xf bound_ctrl:1
	v_fmac_f32_e32 v68, 0.5, v9
	v_add_f32_dpp v66, v66, v66 quad_perm:[2,3,0,1] row_mask:0xf bank_mask:0xf bound_ctrl:1
	v_add_f32_dpp v67, v67, v67 quad_perm:[2,3,0,1] row_mask:0xf bank_mask:0xf bound_ctrl:1
	v_add_f32_dpp v68, v68, v68 quad_perm:[2,3,0,1] row_mask:0xf bank_mask:0xf bound_ctrl:1
	s_and_saveexec_b64 s[2:3], s[0:1]
	s_cbranch_execz .LBB0_707
	ds_add_f32 v190, v66 offset:32
	ds_add_f32 v190, v67 offset:36
	ds_add_f32 v190, v68 offset:40

.LBB0_709:
	s_or_b64 exec, exec, s[2:3]
	v_exp_f32_e32 v12, v12
	v_exp_f32_e32 v13, v13
	v_exp_f32_e32 v14, v14
	v_exp_f32_e32 v15, v15
	v_exp_f32_e32 v10, v10
	v_exp_f32_e32 v11, v11
	v_exp_f32_e32 v16, v16
	v_exp_f32_e32 v17, v17
	v_pk_mul_f32 v[12:13], v[182:183], v[12:13]
	v_pk_mul_f32 v[14:15], v[182:183], v[14:15]
	v_pk_mul_f32 v[10:11], v[182:183], v[10:11]
	v_fma_f32 v67, 0.5, v13, v14
	v_pk_mul_f32 v[16:17], v[182:183], v[16:17]
	v_add_f32_e32 v66, v10, v11
	v_add_f32_e32 v67, v15, v67
	v_add_f32_e32 v66, v12, v66
	v_add_f32_e32 v67, v16, v67
	v_mul_f32_e32 v68, 0.5, v17
	v_fmac_f32_e32 v66, 0.5, v13
	v_fmac_f32_e32 v67, 0.5, v17
	v_mov_b32_dpp v68, v68 quad_perm:[1,0,3,2] row_mask:0xf bank_mask:0xf bound_ctrl:1
	v_add_f32_dpp v66, v66, v66 quad_perm:[1,0,3,2] row_mask:0xf bank_mask:0xf bound_ctrl:1
	v_add_f32_dpp v67, v67, v67 quad_perm:[1,0,3,2] row_mask:0xf bank_mask:0xf bound_ctrl:1
	v_fmac_f32_e32 v68, 0.5, v17
	v_add_f32_dpp v66, v66, v66 quad_perm:[2,3,0,1] row_mask:0xf bank_mask:0xf bound_ctrl:1
	v_add_f32_dpp v67, v67, v67 quad_perm:[2,3,0,1] row_mask:0xf bank_mask:0xf bound_ctrl:1
	v_add_f32_dpp v68, v68, v68 quad_perm:[2,3,0,1] row_mask:0xf bank_mask:0xf bound_ctrl:1
	s_and_saveexec_b64 s[2:3], s[0:1]
	s_cbranch_execz .LBB0_711
	ds_add_f32 v190, v66 offset:48
	ds_add_f32 v190, v67 offset:52
	ds_add_f32 v190, v68 offset:56

; #define CMP_LDK(KF, KT) do { const int kn_ = ((KT) < ntile) ? (KT) : ntile - 1; _Pragma("unroll") for (int s = 0; s < 4; ++s) KF[s] = kb[kn_ * 256 + s * 64]; } while (0)
; #define CMP_LDV(KT) do { _Pragma("unroll") for (int s = 0; s < 4; ++s) vA[s] = vb[(KT) * 256 + s * 64]; } while (0)
; __device__ __forceinline__ void nsa_tile(const Ctx& C, int b, int g, int t0) {
;     ...
;         if (ntile > 0) {
;             bf16x8 kA[4], kB[4], kC[4], vA[4];
;     ...
;             CMP_LDK(kA, 0); CMP_LDK(kB, 1);
; #pragma unroll 1
;             for (int kt = 0; kt < ntile; kt += 3) {
;                 CMP_LDK(kC, kt + 2); CMP_LDV(kt);     __builtin_amdgcn_sched_barrier(0); CMP_P2(kA, vA, kt);     if (kt + 1 >= ntile) break;
;                 CMP_LDK(kA, kt + 3); CMP_LDV(kt + 1); __builtin_amdgcn_sched_barrier(0); CMP_P2(kB, vA, kt + 1); if (kt + 2 >= ntile) break;
;                 CMP_LDK(kB, kt + 4); CMP_LDV(kt + 2); __builtin_amdgcn_sched_barrier(0); CMP_P2(kC, vA, kt + 2);
.LBB0_713:
	s_or_b64 exec, exec, s[2:3]
	v_cvt_pk_bf16_f32 v2, v2, v3
	v_cvt_pk_bf16_f32 v3, v4, v5
	v_cvt_pk_bf16_f32 v4, v6, v7
	v_cvt_pk_bf16_f32 v5, v8, v9
	v_cvt_pk_bf16_f32 v6, v10, v11
	v_cvt_pk_bf16_f32 v7, v12, v13
	s_waitcnt vmcnt(3)
	v_mfma_f32_32x32x16_bf16 v[66:81], v[26:29], v[2:5], v[34:49]
	v_cvt_pk_bf16_f32 v8, v14, v15
	v_cvt_pk_bf16_f32 v9, v16, v17
	s_andn2_b64 vcc, exec, s[24:25]
	s_waitcnt vmcnt(2)
	v_mfma_f32_32x32x16_bf16 v[82:97], v[30:33], v[2:5], v[50:65]
	s_waitcnt vmcnt(1)
	v_mfma_f32_32x32x16_bf16 v[66:81], v[18:21], v[6:9], v[66:81]
	s_waitcnt vmcnt(0)
	v_mfma_f32_32x32x16_bf16 v[82:97], v[22:25], v[6:9], v[82:97]
	s_cbranch_vccnz .LBB0_725
	s_cmp_lt_u32 s58, s16
	s_cselect_b32 s2, s58, s12
	s_lshl_b32 s2, s2, 8
	s_ashr_i32 s3, s2, 31
	v_lshl_add_u64 v[2:3], s[2:3], 4, v[180:181]
	s_add_i32 s6, s18, 0x100
	global_load_dwordx4 v[142:145], v[2:3], off
	global_load_dwordx4 v[138:141], v[2:3], off offset:1024
	global_load_dwordx4 v[134:137], v[2:3], off offset:2048
	global_load_dwordx4 v[130:133], v[2:3], off offset:3072
	v_lshl_add_u64 v[2:3], s[6:7], 4, v[184:185]
	global_load_dwordx4 v[170:173], v[2:3], off
	global_load_dwordx4 v[174:177], v[2:3], off offset:1024
	global_load_dwordx4 v[162:165], v[2:3], off offset:2048
	global_load_dwordx4 v[166:169], v[2:3], off offset:3072
	v_mfma_f32_32x32x16_bf16 v[2:17], v[158:161], v[98:101], v[226:241]
	s_add_i32 s2, s13, 64
	s_cmp_le_i32 s2, s17
	v_mfma_f32_32x32x16_bf16 v[2:17], v[154:157], v[102:105], v[2:17]
	v_mfma_f32_32x32x16_bf16 v[2:17], v[150:153], v[106:109], v[2:17]
	v_mfma_f32_32x32x16_bf16 v[2:17], v[146:149], v[110:113], v[2:17]
	s_cbranch_scc1 .LBB0_716
	v_subrev_u32_e32 v18, 64, v189
	v_cmp_lt_i32_e32 vcc, -1, v18
	v_max_i32_e32 v18, 0, v18
	s_nop 0
	v_cndmask_b32_e32 v19, 64, v218, vcc
	v_cmp_le_u32_e32 vcc, v19, v18
	v_or_b32_e32 v20, 2, v19
	s_nop 3
	v_cndmask_b32_e32 v2, v249, v2, vcc
	v_cmp_lt_u32_e32 vcc, v19, v18
	s_nop 1
	v_cndmask_b32_e32 v3, v249, v3, vcc
	v_cmp_le_u32_e32 vcc, v20, v18
	v_or_b32_e32 v20, 3, v19
	s_nop 0
	v_cndmask_b32_e32 v4, v249, v4, vcc
	v_cmp_le_u32_e32 vcc, v20, v18
	v_or_b32_e32 v20, 4, v19
	s_nop 0
	v_cndmask_b32_e32 v5, v249, v5, vcc
	v_cmp_le_u32_e32 vcc, v20, v18
	v_or_b32_e32 v20, 5, v19
	s_nop 0
	v_cndmask_b32_e32 v6, v249, v6, vcc
	v_cmp_le_u32_e32 vcc, v20, v18
	v_or_b32_e32 v20, 6, v19
	s_nop 0
	v_cndmask_b32_e32 v7, v249, v7, vcc
	v_cmp_le_u32_e32 vcc, v20, v18
	v_or_b32_e32 v20, 7, v19
	s_nop 0
	v_cndmask_b32_e32 v8, v249, v8, vcc
	v_cmp_le_u32_e32 vcc, v20, v18
	v_add_u32_e32 v20, 16, v19
	s_nop 0
	v_cndmask_b32_e32 v9, v249, v9, vcc
	v_cmp_le_u32_e32 vcc, v20, v18
	v_add_u32_e32 v20, 17, v19
	s_nop 0
	v_cndmask_b32_e32 v10, v249, v10, vcc
	v_cmp_le_u32_e32 vcc, v20, v18
	v_add_u32_e32 v20, 18, v19
	s_nop 0
	v_cndmask_b32_e32 v11, v249, v11, vcc
	v_cmp_le_u32_e32 vcc, v20, v18
	v_add_u32_e32 v20, 19, v19
	s_nop 0
	v_cndmask_b32_e32 v12, v249, v12, vcc
	v_cmp_le_u32_e32 vcc, v20, v18
	v_add_u32_e32 v20, 20, v19
	s_nop 0
	v_cndmask_b32_e32 v13, v249, v13, vcc
	v_cmp_le_u32_e32 vcc, v20, v18
	v_add_u32_e32 v20, 21, v19
	s_nop 0
	v_cndmask_b32_e32 v14, v249, v14, vcc
	v_cmp_le_u32_e32 vcc, v20, v18
	v_add_u32_e32 v20, 22, v19
	v_add_u32_e32 v19, 23, v19
	v_cndmask_b32_e32 v15, v249, v15, vcc
	v_cmp_le_u32_e32 vcc, v20, v18
	s_nop 1
	v_cndmask_b32_e32 v16, v249, v16, vcc
	v_cmp_le_u32_e32 vcc, v19, v18
	s_nop 1
	v_cndmask_b32_e32 v17, v249, v17, vcc
.LBB0_716:
	s_nop 10
	v_exp_f32_e32 v4, v4
	v_exp_f32_e32 v5, v5
	v_exp_f32_e32 v6, v6
	v_exp_f32_e32 v7, v7
	v_exp_f32_e32 v2, v2
	v_exp_f32_e32 v3, v3
	v_exp_f32_e32 v8, v8
	v_exp_f32_e32 v9, v9
	v_pk_mul_f32 v[4:5], v[182:183], v[4:5]
	v_pk_mul_f32 v[6:7], v[182:183], v[6:7]
	v_pk_mul_f32 v[2:3], v[182:183], v[2:3]
	v_fma_f32 v19, 0.5, v5, v6
	v_pk_mul_f32 v[8:9], v[182:183], v[8:9]
	v_add_f32_e32 v18, v2, v3
	v_add_f32_e32 v19, v7, v19
	v_add_f32_e32 v18, v4, v18
	v_add_f32_e32 v19, v8, v19
	v_mul_f32_e32 v20, 0.5, v9
	v_fmac_f32_e32 v18, 0.5, v5
	v_fmac_f32_e32 v19, 0.5, v9
	v_mov_b32_dpp v20, v20 quad_perm:[1,0,3,2] row_mask:0xf bank_mask:0xf bound_ctrl:1
	v_add_f32_dpp v18, v18, v18 quad_perm:[1,0,3,2] row_mask:0xf bank_mask:0xf bound_ctrl:1
	v_add_f32_dpp v19, v19, v19 quad_perm:[1,0,3,2] row_mask:0xf bank_mask:0xf bound_ctrl:1
	v_fmac_f32_e32 v20, 0.5, v9
	v_add_f32_dpp v18, v18, v18 quad_perm:[2,3,0,1] row_mask:0xf bank_mask:0xf bound_ctrl:1
	v_add_f32_dpp v19, v19, v19 quad_perm:[2,3,0,1] row_mask:0xf bank_mask:0xf bound_ctrl:1
	v_add_f32_dpp v20, v20, v20 quad_perm:[2,3,0,1] row_mask:0xf bank_mask:0xf bound_ctrl:1
	s_and_saveexec_b64 s[2:3], s[0:1]
	s_cbranch_execz .LBB0_718
	ds_add_f32 v190, v18 offset:64
	ds_add_f32 v190, v19 offset:68
	ds_add_f32 v190, v20 offset:72

.LBB0_720:
	s_or_b64 exec, exec, s[2:3]
	v_exp_f32_e32 v12, v12
	v_exp_f32_e32 v13, v13
	v_exp_f32_e32 v14, v14
	v_exp_f32_e32 v15, v15
	v_exp_f32_e32 v10, v10
	v_exp_f32_e32 v11, v11
	v_exp_f32_e32 v16, v16
	v_exp_f32_e32 v17, v17
	v_pk_mul_f32 v[12:13], v[182:183], v[12:13]
	v_pk_mul_f32 v[14:15], v[182:183], v[14:15]
	v_pk_mul_f32 v[10:11], v[182:183], v[10:11]
	v_fma_f32 v19, 0.5, v13, v14
	v_pk_mul_f32 v[16:17], v[182:183], v[16:17]
	v_add_f32_e32 v18, v10, v11
	v_add_f32_e32 v19, v15, v19
	v_add_f32_e32 v18, v12, v18
	v_add_f32_e32 v19, v16, v19
	v_mul_f32_e32 v20, 0.5, v17
	v_fmac_f32_e32 v18, 0.5, v13
	v_fmac_f32_e32 v19, 0.5, v17
	v_mov_b32_dpp v20, v20 quad_perm:[1,0,3,2] row_mask:0xf bank_mask:0xf bound_ctrl:1
	v_add_f32_dpp v18, v18, v18 quad_perm:[1,0,3,2] row_mask:0xf bank_mask:0xf bound_ctrl:1
	v_add_f32_dpp v19, v19, v19 quad_perm:[1,0,3,2] row_mask:0xf bank_mask:0xf bound_ctrl:1
	v_fmac_f32_e32 v20, 0.5, v17
	v_add_f32_dpp v18, v18, v18 quad_perm:[2,3,0,1] row_mask:0xf bank_mask:0xf bound_ctrl:1
	v_add_f32_dpp v19, v19, v19 quad_perm:[2,3,0,1] row_mask:0xf bank_mask:0xf bound_ctrl:1
	v_add_f32_dpp v20, v20, v20 quad_perm:[2,3,0,1] row_mask:0xf bank_mask:0xf bound_ctrl:1
	s_and_saveexec_b64 s[2:3], s[0:1]
	s_cbranch_execz .LBB0_722
	ds_add_f32 v190, v18 offset:80
	ds_add_f32 v190, v19 offset:84
	ds_add_f32 v190, v20 offset:88
